# fast-tile dispatch at the loop head with one test; HGRN2 output gain vectors loaded once per wave
# speedup vs baseline: 1.0240x; 1.0034x over previous
; #define LAS __attribute__((address_space(3)))
; #define ATT_LOAD(t) do { const int tw_ = DIFF ? (t) : ((t) & 3); const bf16* Kt_ = Kh + (kvrow0 + (size_t)tw_ * 64) * kvpitch; const bf16* Vt_ = Vh + (kvrow0 + (size_t)tw_ * 64) * kvpitch; \
;         _Pragma("unroll") for (int i_ = 0; i_ < 2; ++i_) { kreg[i_] = *(const bf16x8*)(Kt_ + loff + 32 * i_ * kvpitch); vreg[i_] = *(const bf16x8*)(Vt_ + loff + 32 * i_ * kvpitch); } } while (0)
; #define ATT_STORE(ks, vs) do { _Pragma("unroll") for (int i_ = 0; i_ < 2; ++i_) { const int kv_ = skv0 + 32 * i_; \
;         *(LAS bf16x8*)(L + (ks) * KSLOT + (kv_ * KP + scol) * 2) = kreg[i_]; *(LAS bf16x8*)(L + 2 * KSLOT + (vs) * VSLOT + (kv_ * VP + scol) * 2) = vreg[i_]; } } while (0)
; template <bool DIFF> DI void attn_unit(LAS unsigned char* L, const bf16* Qh, int qpitch, const bf16* Kh, const bf16* Vh, int kvpitch, bf16* Oh, int opitch, ...
;     ...
;     for (int t = 0; t < NT; ++t) {
;         const int cur = t & 1, vnext = (vcur == 2) ? 0 : vcur + 1;
;         if (t + 1 < NT) ATT_STORE(cur ^ 1, vnext);
;         if (t + 2 < NT) ATT_LOAD(t + 2);
;         const LAS unsigned char* Kc = L + cur * KSLOT + koff;
;         const bool act0 = !DIFF || (64 * t <= qlast), act1 = !DIFF || (64 * t + 32 <= qlast);
;         if (stag && pa0) att_pv(L + voff + vprev * VSLOT, pf, y, pa1);
;         if (act0) att_qk_softmax<DIFF, ND0>(Kc, qf, tbl, t, qbase, r, h_, act1, m_run, l_run, negm, y, pf);
.LBB0_191:
	s_add_i32 s96, s87, -1
	s_and_b32 s8, s96, 1
	s_add_i32 s36, s94, 1
	s_cmp_lg_u32 s94, 2
	s_mov_b32 s95, s94
	s_cselect_b32 s94, s36, 0
	s_cmpk_gt_i32 s84, 0x7f
	s_cbranch_scc1 .Lfast
	s_and_b64 s[28:29], s[16:17], s[28:29]
	s_andn2_b64 vcc, exec, s[28:29]
	s_cbranch_vccnz .LBB0_199

; #define LAS __attribute__((address_space(3)))
; template <bool DIFF, int ND0> DI void att_qk_softmax(const LAS unsigned char* Kc, const bf16x8 (&qf)[ND0], const LAS float* tbl, int t, int qbase, int r, int h_, bool act1, ...
;     ...
;     for (int sub = 0; sub < 2; ++sub) {
;         p[sub] = negm;
;         if (sub == 0 || act1) {
; #pragma unroll
;             for (int d0 = 0; d0 < ND0; ++d0) { const bf16x8 kf = *(const LAS bf16x8*)(Kc + (32 * sub * ATT_KP + 16 * d0) * 2);
;                 p[sub] = __builtin_amdgcn_mfma_f32_32x32x16_bf16(kf, qf[d0], p[sub], 0, 0, 0); }
;         }
;     }
; template <bool DIFF> DI void attn_unit(LAS unsigned char* L, const bf16* Qh, int qpitch, const bf16* Kh, const bf16* Vh, int kvpitch, bf16* Oh, int opitch, ...
;     ...
;         const bool act0 = !DIFF || (64 * t <= qlast), act1 = !DIFF || (64 * t + 32 <= qlast);
.LBB0_198:
.LBB0_199:
	s_cmp_le_i32 s25, s81
	s_cselect_b64 s[28:29], -1, 0
	s_cmp_lt_i32 s25, s1
	s_cselect_b64 s[26:27], -1, 0
	v_cndmask_b32_e64 v220, 0, 1, s[26:27]
	s_cmp_gt_i32 s25, s81
	s_cbranch_scc1 .Lstage
	s_mulk_i32 s8, 0x4400
	v_add_u32_e32 v221, s8, v216
	ds_read_b128 v[96:99], v221
	ds_read_b128 v[100:103], v221 offset:32
	ds_read_b128 v[104:107], v221 offset:64
	ds_read_b128 v[108:111], v221 offset:96
	s_andn2_b64 vcc, exec, s[26:27]
	s_cbranch_vccnz .Lqk_half
	ds_read_b128 v[222:225], v221 offset:8704
	ds_read_b128 v[226:229], v221 offset:8736
	ds_read_b128 v[230:233], v221 offset:8768
	ds_read_b128 v[234:237], v221 offset:8800
	s_waitcnt lgkmcnt(7)
	v_mfma_f32_32x32x16_bf16 v[80:95], v[96:99], v[112:115], v[64:79]
	s_waitcnt lgkmcnt(6)
	v_mfma_f32_32x32x16_bf16 v[80:95], v[100:103], v[116:119], v[80:95]
	s_waitcnt lgkmcnt(5)
	v_mfma_f32_32x32x16_bf16 v[80:95], v[104:107], v[120:123], v[80:95]
	s_waitcnt lgkmcnt(4)
	v_mfma_f32_32x32x16_bf16 v[80:95], v[108:111], v[124:127], v[80:95]
	s_waitcnt lgkmcnt(3)
	v_mfma_f32_32x32x16_bf16 v[96:111], v[222:225], v[112:115], v[64:79]
	s_waitcnt lgkmcnt(2)
	v_mfma_f32_32x32x16_bf16 v[96:111], v[226:229], v[116:119], v[96:111]
	s_waitcnt lgkmcnt(1)
	v_mfma_f32_32x32x16_bf16 v[96:111], v[230:233], v[120:123], v[96:111]
	s_waitcnt lgkmcnt(0)
	v_mfma_f32_32x32x16_bf16 v[96:111], v[234:237], v[124:127], v[96:111]
	s_branch .Lstage

; template <bool DIFF, int ND0> DI void att_qk_softmax(const LAS unsigned char* Kc, const bf16x8 (&qf)[ND0], const LAS float* tbl, int t, int qbase, int r, int h_, bool act1, ...
;     ...
;     if (t == 0 || __any(mx > 8.f)) {
;         const float dl = (t == 0) ? mx : fmaxf(mx, 0.f), alpha = __builtin_amdgcn_exp2f(-dl);
;         m_run += dl; l_run *= alpha;
; #pragma unroll
;         for (int i = 0; i < 16; ++i) { negm[i] = -m_run; p[0][i] -= dl; p[1][i] -= dl; }
; #pragma unroll
;         for (int d0 = 0; d0 < 4; ++d0)
; #pragma unroll
;             for (int i = 0; i < 16; ++i) y[d0][i] *= alpha;
;     }
.Lfast_resc:
	s_mov_b64 s[28:29], -1
	s_mov_b64 s[26:27], -1
	v_mov_b32_e32 v220, 1
	s_branch .LBB0_204

; DI void hg_out_units(LAS unsigned char* L, int u0, int G, const float* LOGF, const bf16* QHG, const bf16* IHG, const bf16* GHG, const bf16* ST, const float* og, bf16* MIX, int tid, int wave, int lane) {
;     ...
;     const int c = tid & 127, seg = tid >> 7;
;     const int lr = lane & 15, quad = lane >> 4, tt = wave >> 1, dh = wave & 1;
;     int unit = u0; if (unit >= 2048) return;
;     float g[16]; bf16 qraw[16]; bf16x8 v8[2];
;     ...
;     HGO_LOAD(unit);
.LBB0_332:
	s_or_b64 exec, exec, s[0:1]
	s_mov_b32 s0, -1
	s_waitcnt lgkmcnt(0)
	s_barrier
	s_mov_b64 s[24:25], 0
	v_mbcnt_lo_u32_b32 v0, s0, 0
	v_mbcnt_hi_u32_b32 v0, s0, v0
	v_add_u32_e32 v8, s68, v0
	s_and_b64 vcc, exec, s[4:5]
	v_readfirstlane_b32 s0, v8
	s_cbranch_vccnz .LBB0_352
	v_readlane_b32 s4, v252, 0
	v_mov_b64_e32 v[0:1], s[24:25]
	v_readlane_b32 s5, v252, 1
	v_readlane_b32 s6, v252, 2
	v_readlane_b32 s7, v252, 3
	s_mov_b64 s[4:5], 0x1b000000
	s_lshl_b32 s36, s46, 7
	v_lshl_add_u64 v[84:85], s[6:7], 0, v[0:1]
	v_lshl_add_u64 v[86:87], v[84:85], 0, s[4:5]
	s_mov_b64 s[4:5], 0x11000000
	v_lshl_add_u64 v[88:89], v[84:85], 0, s[4:5]
	s_mov_b64 s[4:5], 0x19000000
	v_readlane_b32 s8, v252, 39
	v_lshl_add_u64 v[90:91], v[84:85], 0, s[4:5]
	s_lshl_b64 s[4:5], s[36:37], 2
	v_readlane_b32 s10, v252, 41
	v_readlane_b32 s11, v252, 42
	s_add_u32 s68, s10, s4
	s_addc_u32 s69, s11, s5
	s_mov_b64 s[4:5], 0x17000000
	v_ashrrev_i32_e32 v23, 7, v8
	v_lshl_add_u64 v[10:11], v[84:85], 0, s[4:5]
	v_lshlrev_b32_e32 v92, 4, v23
	v_readlane_b32 s4, v253, 21
	v_ashrrev_i32_e32 v93, 31, v92
	v_readlane_b32 s5, v253, 22
	s_waitcnt vmcnt(3)
	v_and_b32_e32 v128, 0x7f, v8
	v_readlane_b32 s6, v253, 24
	v_lshl_add_u64 v[0:1], s[4:5], 0, v[92:93]
	v_lshlrev_b64 v[0:1], 10, v[0:1]
	v_or3_b32 v0, v128, s6, v0
	v_lshl_add_u64 v[2:3], v[0:1], 2, v[86:87]
	v_or_b32_e32 v6, 0x400, v0
	v_mov_b32_e32 v7, v1
	v_or_b32_e32 v14, 0x800, v0
	v_mov_b32_e32 v15, v1
	v_or_b32_e32 v18, 0xc00, v0
	v_mov_b32_e32 v19, v1
	v_lshl_add_u64 v[4:5], v[0:1], 1, v[88:89]
	v_lshl_add_u64 v[12:13], v[6:7], 2, v[86:87]
	v_lshl_add_u64 v[6:7], v[6:7], 1, v[88:89]
	v_lshl_add_u64 v[16:17], v[14:15], 2, v[86:87]
	v_lshl_add_u64 v[14:15], v[14:15], 1, v[88:89]
	v_lshl_add_u64 v[20:21], v[18:19], 2, v[86:87]
	v_lshl_add_u64 v[18:19], v[18:19], 1, v[88:89]
	global_load_dword v129, v[2:3], off
	global_load_ushort v130, v[4:5], off
	global_load_dword v131, v[12:13], off
	global_load_ushort v132, v[6:7], off
	global_load_dword v133, v[16:17], off
	global_load_ushort v134, v[14:15], off
	global_load_dword v135, v[20:21], off
	global_load_ushort v136, v[18:19], off
	v_or_b32_e32 v2, 0x1000, v0
	v_mov_b32_e32 v3, v1
	v_lshl_add_u64 v[4:5], v[2:3], 2, v[86:87]
	v_lshl_add_u64 v[2:3], v[2:3], 1, v[88:89]
	v_or_b32_e32 v6, 0x1400, v0
	v_mov_b32_e32 v7, v1
	v_or_b32_e32 v14, 0x1800, v0
	v_mov_b32_e32 v15, v1
	v_or_b32_e32 v18, 0x1c00, v0
	v_mov_b32_e32 v19, v1
	v_lshl_add_u64 v[12:13], v[6:7], 2, v[86:87]
	v_lshl_add_u64 v[6:7], v[6:7], 1, v[88:89]
	v_lshl_add_u64 v[16:17], v[14:15], 2, v[86:87]
	v_lshl_add_u64 v[14:15], v[14:15], 1, v[88:89]
	v_lshl_add_u64 v[20:21], v[18:19], 2, v[86:87]
	v_lshl_add_u64 v[18:19], v[18:19], 1, v[88:89]
	global_load_dword v137, v[4:5], off
	global_load_ushort v138, v[2:3], off
	global_load_dword v139, v[12:13], off
	global_load_ushort v140, v[6:7], off
	global_load_dword v142, v[16:17], off
	global_load_ushort v144, v[14:15], off
	global_load_dword v148, v[20:21], off
	global_load_ushort v150, v[18:19], off
	v_or_b32_e32 v2, 0x2000, v0
	v_mov_b32_e32 v3, v1
	v_lshl_add_u64 v[4:5], v[2:3], 2, v[86:87]
	v_lshl_add_u64 v[2:3], v[2:3], 1, v[88:89]
	v_or_b32_e32 v6, 0x2400, v0
	v_mov_b32_e32 v7, v1
	v_or_b32_e32 v14, 0x2800, v0
	v_mov_b32_e32 v15, v1
	v_or_b32_e32 v18, 0x2c00, v0
	v_mov_b32_e32 v19, v1
	v_lshl_add_u64 v[12:13], v[6:7], 2, v[86:87]
	v_lshl_add_u64 v[6:7], v[6:7], 1, v[88:89]
	v_lshl_add_u64 v[16:17], v[14:15], 2, v[86:87]
	v_lshl_add_u64 v[14:15], v[14:15], 1, v[88:89]
	v_lshl_add_u64 v[20:21], v[18:19], 2, v[86:87]
	v_lshl_add_u64 v[18:19], v[18:19], 1, v[88:89]
	global_load_dword v152, v[4:5], off
	global_load_ushort v153, v[2:3], off
	global_load_dword v154, v[12:13], off
	global_load_ushort v155, v[6:7], off
	global_load_dword v156, v[16:17], off
	global_load_ushort v170, v[14:15], off
	global_load_dword v173, v[20:21], off
	global_load_ushort v174, v[18:19], off
	v_or_b32_e32 v2, 0x3000, v0
	v_mov_b32_e32 v3, v1
	v_lshl_add_u64 v[4:5], v[2:3], 2, v[86:87]
	v_or_b32_e32 v6, 0x3400, v0
	v_mov_b32_e32 v7, v1
	v_or_b32_e32 v14, 0x3800, v0
	v_mov_b32_e32 v15, v1
	v_or_b32_e32 v0, 0x3c00, v0
	v_lshl_add_u64 v[2:3], v[2:3], 1, v[88:89]
	v_lshl_add_u64 v[12:13], v[6:7], 2, v[86:87]
	v_lshl_add_u64 v[6:7], v[6:7], 1, v[88:89]
	v_lshl_add_u64 v[16:17], v[14:15], 2, v[86:87]
	v_lshl_add_u64 v[14:15], v[14:15], 1, v[88:89]
	v_lshl_add_u64 v[18:19], v[0:1], 2, v[86:87]
	v_lshl_add_u64 v[0:1], v[0:1], 1, v[88:89]
	global_load_dword v175, v[4:5], off
	global_load_ushort v176, v[2:3], off
	global_load_dword v177, v[12:13], off
	global_load_ushort v178, v[6:7], off
	global_load_dword v179, v[16:17], off
	global_load_ushort v180, v[14:15], off
	global_load_dword v181, v[18:19], off
	global_load_ushort v182, v[0:1], off
	v_add_u32_e32 v4, 0x200, v8
	v_ashrrev_i32_e32 v94, 4, v8
	v_ashrrev_i32_e32 v96, 4, v4
	s_lshl_b32 s36, s6, 1
	v_lshlrev_b32_e32 v2, 4, v8
	v_ashrrev_i32_e32 v95, 31, v94
	v_ashrrev_i32_e32 v97, 31, v96
	v_lshl_add_u64 v[0:1], v[10:11], 0, s[36:37]
	v_and_b32_e32 v160, 0xf0, v2
	v_lshl_add_u64 v[2:3], s[4:5], 0, v[94:95]
	v_lshl_add_u64 v[4:5], s[4:5], 0, v[96:97]
	v_lshl_add_u64 v[0:1], v[0:1], 0, v[160:161]
	v_lshlrev_b64 v[2:3], 11, v[2:3]
	v_lshlrev_b64 v[4:5], 11, v[4:5]
	v_lshl_add_u64 v[2:3], v[0:1], 0, v[2:3]
	v_lshl_add_u64 v[4:5], v[0:1], 0, v[4:5]
	global_load_dwordx4 v[0:3], v[2:3], off
	s_nop 0
	global_load_dwordx4 v[4:7], v[4:5], off
	v_readlane_b32 s22, v252, 53
	s_ashr_i32 s1, s0, 6
	s_ashr_i32 s22, s0, 7
	v_readlane_b32 s23, v252, 54
	v_and_b32_e32 v22, 15, v8
	s_and_b32 s74, s1, 1
	s_lshl_b32 s4, s22, 4
	s_lshl_b32 s1, s1, 1
	v_or_b32_e32 v98, s4, v22
	s_and_b32 s23, s1, 2
	s_movk_i32 s1, 0x90
	s_and_b32 s0, s0, 0xffffff80
	s_lshl_b32 s6, s74, 2
	v_mul_lo_u32 v16, v98, s1
	v_readlane_b32 s1, v254, 60
	s_add_i32 s0, s0, 0
	s_add_i32 s0, s0, s6
	v_add_u32_e32 v145, s1, v16
	s_movk_i32 s1, 0x110
	v_and_b32_e32 v9, 63, v8
	v_mul_lo_u32 v17, v98, s1
	s_add_i32 s0, s0, 0x14800
	v_bfe_u32 v24, v8, 4, 2
	s_ashr_i32 s5, s4, 31
	s_add_i32 s4, 0, 0x14000
	v_and_b32_e32 v100, 48, v8
	v_add_u32_e32 v17, 0, v17
	s_lshl_b32 s1, s74, 7
	v_lshl_add_u32 v149, v9, 3, s0
	s_lshl_b32 s36, s74, 6
	s_movk_i32 s0, 0x140
	v_lshlrev_b32_e32 v13, 3, v8
	v_lshlrev_b32_e32 v14, 3, v24
	s_waitcnt vmcnt(34)
; DI void hg_out_units(LAS unsigned char* L, int u0, int G, const float* LOGF, const bf16* QHG, const bf16* IHG, const bf16* GHG, const bf16* ST, const float* og, bf16* MIX, int tid, int wave, int lane) {
;     ...
;     const int c = tid & 127, seg = tid >> 7;
;     const int lr = lane & 15, quad = lane >> 4, tt = wave >> 1, dh = wave & 1;
;     int unit = u0; if (unit >= 2048) return;
;     float g[16]; bf16 qraw[16]; bf16x8 v8[2];
;     ...
;     HGO_LOAD(unit);
;     ...
;     for (int d = 0; d < 4; ++d) { const int dv0 = 16 * (4 * dh + d) + quad * 4;
;         const u32x2 gt = gtv[d]; const f32x4 gn = *(const f32x4*)(og + dv0);
	v_lshl_add_u32 v141, v8, 2, s4
	v_add_u32_e32 v147, v17, v100
	v_bfe_u32 v8, v8, 2, 2
	s_add_i32 s1, s1, 0
	s_or_b32 s75, s36, 16
	s_or_b32 s81, s36, 32
	s_or_b32 s84, s36, 48
	v_mul_lo_u32 v17, v94, s0
	v_mul_lo_u32 v18, v96, s0
	s_movk_i32 s0, 0x880
	v_readlane_b32 s14, v252, 45
	v_add_u32_e32 v146, v145, v14
	v_or_b32_e32 v14, v14, v8
	v_and_b32_e32 v8, 24, v13
	v_lshl_add_u64 v[102:103], v[10:11], 0, v[160:161]
	v_mul_lo_u32 v10, v23, s0
	s_cmp_le_i32 s23, s22
	v_add_u32_e32 v13, s1, v8
	v_or_b32_e32 v10, v10, v128
	s_cselect_b64 s[0:1], -1, 0
	s_lshl_b32 s14, s23, 4
	v_lshlrev_b32_e32 v12, 2, v24
	v_lshl_add_u32 v151, v10, 1, 0
	v_or_b32_e32 v10, s14, v22
	s_lshl_b32 s93, s23, 5
	s_or_b32 s80, s23, 1
	v_readlane_b32 s15, v252, 46
	v_readlane_b32 s16, v252, 47
	v_readlane_b32 s17, v252, 48
	v_mul_u32_u24_e32 v19, 0x110, v10
	v_or_b32_e32 v10, s14, v12
	s_cmp_lt_i32 s23, s22
	v_readlane_b32 s20, v252, 51
	v_readlane_b32 s21, v252, 52
	v_cmp_gt_i32_e64 s[14:15], v10, v98
	v_cmp_lt_i32_e64 s[16:17], v10, v98
	v_or_b32_e32 v11, 2, v10
	v_or_b32_e32 v10, 3, v10
	s_cselect_b64 s[34:35], -1, 0
	s_lshl_b32 s22, s80, 4
	v_cmp_gt_i32_e64 s[20:21], v10, v98
	v_or_b32_e32 v10, s22, v22
	v_readlane_b32 s18, v252, 49
	v_readlane_b32 s19, v252, 50
	v_or_b32_e32 v8, s36, v12
	v_mul_u32_u24_e32 v20, 0x110, v10
	v_or_b32_e32 v10, s22, v12
	v_add_u32_e32 v15, 0, v160
	v_cmp_gt_i32_e64 s[18:19], v11, v98
	v_cmp_gt_i32_e64 s[22:23], v10, v98
	v_cmp_lt_i32_e64 s[62:63], v10, v98
	v_or_b32_e32 v11, 2, v10
	v_or_b32_e32 v10, 3, v10
	v_lshlrev_b32_e32 v160, 2, v8
	v_mov_b32_e32 v101, v161
	v_mov_b32_e32 v99, s5
	v_lshl_add_u32 v143, v128, 2, s4
	v_cmp_gt_u32_e64 s[4:5], 16, v9
	v_lshlrev_b32_e32 v9, 3, v98
	v_cmp_gt_i32_e64 s[26:27], v11, v98
	v_cmp_gt_i32_e64 s[28:29], v10, v98
	v_lshl_add_u64 v[104:105], s[68:69], 0, v[160:161]
	s_lshl_b32 s68, s74, 14
	v_lshl_add_u64 v[10:11], s[24:25], 0, v[100:101]
	v_readlane_b32 s24, v254, 30
	v_readlane_b32 s9, v252, 40
	v_readlane_b32 s12, v252, 43
	v_readlane_b32 s13, v252, 44
	v_add_u32_e32 v16, 0, v100
	v_mul_u32_u24_e32 v14, 0x140, v14
	v_lshl_or_b32 v21, v22, 8, s68
	v_readlane_b32 s25, v254, 31
	s_lshl_b32 s74, s84, 1
	v_add_u32_e32 v9, 0, v9
	v_readlane_b32 s84, v254, 36
	v_cmp_lt_i32_e64 s[6:7], 0, v23
	v_cmp_lt_i32_e64 s[8:9], 1, v23
	v_cmp_lt_i32_e64 s[10:11], 2, v23
	v_cmp_lt_i32_e64 s[12:13], 3, v23
	s_lshl_b32 s94, s80, 5
	v_or_b32_e32 v106, 0x7000080, v21
	v_mov_b32_e32 v107, v161
	v_lshl_add_u64 v[108:109], s[24:25], 0, v[10:11]
	v_or_b32_e32 v110, 0x7003080, v21
	v_mov_b32_e32 v111, v161
	v_or_b32_e32 v112, 0x7002080, v21
	v_mov_b32_e32 v113, v161
	v_or_b32_e32 v114, 0x7001080, v21
	v_mov_b32_e32 v115, v161
	v_lshlrev_b32_e32 v160, 1, v12
	s_lshl_b32 s80, s36, 1
	s_lshl_b32 s24, s75, 1
	s_lshl_b32 s68, s81, 1
	v_add_u32_e32 v101, v15, v17
	v_add_u32_e32 v157, v15, v18
	v_add_u32_e32 v158, v16, v19
	v_add_u32_e32 v159, v16, v20
	v_add_u32_e32 v171, v13, v14
	v_add_u32_e32 v172, 0x14800, v9
	v_lshlrev_b32_e32 v116, 1, v8
	v_readlane_b32 s95, v253, 23
	v_readlane_b32 s96, v253, 20
	s_mov_b32 s97, s84
	v_readlane_b32 s85, v254, 37
	global_load_dwordx4 v[208:211], v[104:105], off
	global_load_dwordx4 v[212:215], v[104:105], off offset:64
	global_load_dwordx4 v[216:219], v[104:105], off offset:128
	global_load_dwordx4 v[220:223], v[104:105], off offset:192
	s_branch .LBB0_335
; DI unsigned pk2(float lo, float hi) { f32x2_t v = {lo, hi}; bf16x2_t b = __builtin_convertvector(v, bf16x2_t); return __builtin_bit_cast(unsigned, b); }
; DI float fexp(float x) { return __builtin_amdgcn_exp2f(x * LOG2E); }
; DI void hg_out_units(LAS unsigned char* L, int u0, int G, const float* LOGF, const bf16* QHG, const bf16* IHG, const bf16* GHG, const bf16* ST, const float* og, bf16* MIX, int tid, int wave, int lane) {
;     ...
;     __syncthreads();
;     const float r = rsqrtf((ssq[(16 * tt + lr) * 2] + ssq[(16 * tt + lr) * 2 + 1]) * (1.f / 128.f) + EPS);
;     const size_t tok = tok0 + 16 * tt + lr;
; #pragma unroll
;     for (int d = 0; d < 4; ++d) { const int dv0 = 16 * (4 * dh + d) + quad * 4;
;         const u32x2 gt = gtv[d]; const f32x4 gn = *(const f32x4*)(og + dv0);
;         float gv[4] = {__uint_as_float(gt.x << 16), __uint_as_float(gt.x & 0xffff0000u), __uint_as_float(gt.y << 16), __uint_as_float(gt.y & 0xffff0000u)};
;         float o[4];
; #pragma unroll
;         for (int j = 0; j < 4; ++j) o[j] = acc[d][j] * r * gn[j] * gv[j] * __builtin_amdgcn_rcpf(1.f + fexp(-gv[j]));
;         u32x2 w; w.x = pk2(o[0], o[1]); w.y = pk2(o[2], o[3]); *(u32x2*)(MIX + tok * DM + 1024 + h * 128 + dv0) = w; }
.LBB0_334:
	s_or_b64 exec, exec, vcc
	v_lshlrev_b64 v[14:15], 12, v[126:127]
	v_lshl_add_u64 v[14:15], v[84:85], 0, v[14:15]
	s_waitcnt lgkmcnt(0)
	s_barrier
	v_lshl_add_u64 v[18:19], v[14:15], 0, s[36:37]
	ds_read_b64 v[12:13], v172
	v_lshlrev_b32_e32 v20, 16, v124
	v_and_b32_e32 v21, 0xffff0000, v124
	v_mov_b32_e32 v117, v161
	s_mov_b64 s[84:85], 0xb000800
	s_waitcnt lgkmcnt(0)
	v_add_f32_e32 v12, v12, v13
	v_fmamk_f32 v12, v12, 0x3c000000, v203
	v_cmp_gt_f32_e32 vcc, s2, v12
	v_mul_f32_e32 v13, 0x4b800000, v12
	s_mov_b32 s25, 0xb000000
	v_cndmask_b32_e32 v12, v12, v13, vcc
	v_rsq_f32_e32 v12, v12
	s_add_i32 s95, s95, s40
	v_readlane_b32 s40, v254, 40
	v_readlane_b32 s41, v254, 41
	v_mul_f32_e32 v13, 0x45800000, v12
	v_cndmask_b32_e32 v12, v12, v13, vcc
	v_mul_f32_e32 v13, 0xbfb8aa3b, v20
	v_exp_f32_e32 v13, v13
	v_lshl_add_u64 v[108:109], v[108:109], 0, s[40:41]
	v_add_f32_e32 v13, 1.0, v13
	v_rcp_f32_e32 v22, v13
	v_pk_mul_f32 v[28:29], v[44:45], v[12:13] op_sel_hi:[1,0]
	v_mul_f32_e32 v13, 0xbfb8aa3b, v21
	v_exp_f32_e32 v13, v13
	s_waitcnt vmcnt(0)
	v_pk_mul_f32 v[14:15], v[208:209], v[28:29]
	s_nop 0
	v_pk_mul_f32 v[14:15], v[14:15], v[20:21]
	v_add_f32_e32 v13, 1.0, v13
	v_lshlrev_b32_e32 v20, 16, v125
	v_rcp_f32_e32 v23, v13
	v_mul_f32_e32 v13, 0xbfb8aa3b, v20
	v_exp_f32_e32 v13, v13
	v_and_b32_e32 v21, 0xffff0000, v125
	v_pk_mul_f32 v[14:15], v[22:23], v[14:15]
	v_add_f32_e32 v13, 1.0, v13
	v_rcp_f32_e32 v22, v13
	v_pk_mul_f32 v[28:29], v[46:47], v[12:13] op_sel_hi:[1,0]
	v_mul_f32_e32 v13, 0xbfb8aa3b, v21
	v_exp_f32_e32 v13, v13
	v_pk_mul_f32 v[16:17], v[210:211], v[28:29]
	v_add_f32_e32 v13, 1.0, v13
	v_rcp_f32_e32 v23, v13
	v_pk_mul_f32 v[16:17], v[16:17], v[20:21]
	v_cvt_pk_bf16_f32 v20, v14, v15
	v_pk_mul_f32 v[16:17], v[22:23], v[16:17]
	s_nop 0
	v_cvt_pk_bf16_f32 v21, v16, v17
	v_lshl_add_u64 v[16:17], v[18:19], 0, v[116:117]
	v_lshl_add_u64 v[14:15], v[16:17], 0, s[84:85]
	v_add_co_u32_e32 v16, vcc, s25, v16
	v_readlane_b32 s25, v254, 24
	s_nop 0
	v_addc_co_u32_e32 v17, vcc, 0, v17, vcc
	global_store_dwordx2 v[16:17], v[20:21], off offset:2048
	v_lshlrev_b32_e32 v20, 16, v122
	v_mul_f32_e32 v13, 0xbfb8aa3b, v20
	v_exp_f32_e32 v13, v13
	v_and_b32_e32 v21, 0xffff0000, v122
	s_add_i32 s96, s96, s25
	s_andn2_b64 vcc, exec, s[86:87]
	v_add_f32_e32 v13, 1.0, v13
	v_rcp_f32_e32 v22, v13
	v_pk_mul_f32 v[28:29], v[32:33], v[12:13] op_sel_hi:[1,0]
	v_mul_f32_e32 v13, 0xbfb8aa3b, v21
	v_exp_f32_e32 v13, v13
	s_waitcnt vmcnt(0)
	v_pk_mul_f32 v[16:17], v[212:213], v[28:29]
	s_nop 0
	v_pk_mul_f32 v[16:17], v[16:17], v[20:21]
	v_add_f32_e32 v13, 1.0, v13
	v_lshlrev_b32_e32 v20, 16, v123
	v_rcp_f32_e32 v23, v13
	v_mul_f32_e32 v13, 0xbfb8aa3b, v20
	v_exp_f32_e32 v13, v13
	v_and_b32_e32 v21, 0xffff0000, v123
	v_pk_mul_f32 v[16:17], v[22:23], v[16:17]
	v_add_f32_e32 v13, 1.0, v13
	v_rcp_f32_e32 v22, v13
	v_pk_mul_f32 v[28:29], v[34:35], v[12:13] op_sel_hi:[1,0]
	v_mul_f32_e32 v13, 0xbfb8aa3b, v21
	v_exp_f32_e32 v13, v13
	v_pk_mul_f32 v[18:19], v[214:215], v[28:29]
	v_cvt_pk_bf16_f32 v16, v16, v17
	v_pk_mul_f32 v[18:19], v[18:19], v[20:21]
	v_add_f32_e32 v13, 1.0, v13
	v_rcp_f32_e32 v23, v13
	v_lshlrev_b32_e32 v20, 16, v120
	v_mul_f32_e32 v13, 0xbfb8aa3b, v20
	v_exp_f32_e32 v13, v13
	v_pk_mul_f32 v[18:19], v[22:23], v[18:19]
	v_and_b32_e32 v21, 0xffff0000, v120
	v_cvt_pk_bf16_f32 v17, v18, v19
	global_store_dwordx2 v[14:15], v[16:17], off offset:32
	v_add_f32_e32 v13, 1.0, v13
	v_rcp_f32_e32 v22, v13
	v_pk_mul_f32 v[24:25], v[24:25], v[12:13] op_sel_hi:[1,0]
	v_mul_f32_e32 v13, 0xbfb8aa3b, v21
	v_exp_f32_e32 v13, v13
	s_waitcnt vmcnt(0)
	v_pk_mul_f32 v[16:17], v[216:217], v[24:25]
	s_nop 0
	v_pk_mul_f32 v[16:17], v[16:17], v[20:21]
	v_add_f32_e32 v13, 1.0, v13
	v_lshlrev_b32_e32 v20, 16, v121
	v_rcp_f32_e32 v23, v13
	v_mul_f32_e32 v13, 0xbfb8aa3b, v20
	v_exp_f32_e32 v13, v13
	v_and_b32_e32 v21, 0xffff0000, v121
	v_pk_mul_f32 v[16:17], v[22:23], v[16:17]
	v_add_f32_e32 v13, 1.0, v13
	v_rcp_f32_e32 v22, v13
	v_pk_mul_f32 v[24:25], v[26:27], v[12:13] op_sel_hi:[1,0]
	v_mul_f32_e32 v13, 0xbfb8aa3b, v21
	v_exp_f32_e32 v13, v13
	v_pk_mul_f32 v[18:19], v[218:219], v[24:25]
	v_cvt_pk_bf16_f32 v16, v16, v17
	v_pk_mul_f32 v[18:19], v[18:19], v[20:21]
	v_add_f32_e32 v13, 1.0, v13
	v_rcp_f32_e32 v23, v13
	v_lshlrev_b32_e32 v20, 16, v118
	v_mul_f32_e32 v13, 0xbfb8aa3b, v20
	v_exp_f32_e32 v13, v13
	v_pk_mul_f32 v[18:19], v[22:23], v[18:19]
	v_and_b32_e32 v21, 0xffff0000, v118
	v_cvt_pk_bf16_f32 v17, v18, v19
	global_store_dwordx2 v[14:15], v[16:17], off offset:64
	v_add_f32_e32 v13, 1.0, v13
	v_rcp_f32_e32 v22, v13
	v_pk_mul_f32 v[8:9], v[8:9], v[12:13] op_sel_hi:[1,0]
	v_mul_f32_e32 v13, 0xbfb8aa3b, v21
	v_exp_f32_e32 v13, v13
	s_waitcnt vmcnt(0)
	v_pk_mul_f32 v[8:9], v[220:221], v[8:9]
	v_add_f32_e32 v13, 1.0, v13
	v_lshlrev_b32_e32 v16, 16, v119
	v_rcp_f32_e32 v23, v13
	v_mul_f32_e32 v13, 0xbfb8aa3b, v16
	v_exp_f32_e32 v13, v13
	v_and_b32_e32 v17, 0xffff0000, v119
	v_pk_mul_f32 v[8:9], v[8:9], v[20:21]
	v_add_f32_e32 v13, 1.0, v13
	v_pk_mul_f32 v[10:11], v[10:11], v[12:13] op_sel_hi:[1,0]
	v_mul_f32_e32 v12, 0xbfb8aa3b, v17
	v_exp_f32_e32 v12, v12
	v_rcp_f32_e32 v20, v13
	v_pk_mul_f32 v[10:11], v[222:223], v[10:11]
	v_pk_mul_f32 v[8:9], v[22:23], v[8:9]
	v_add_f32_e32 v12, 1.0, v12
	v_rcp_f32_e32 v21, v12
	v_pk_mul_f32 v[10:11], v[10:11], v[16:17]
	v_cvt_pk_bf16_f32 v8, v8, v9
	v_pk_mul_f32 v[10:11], v[20:21], v[10:11]
	s_nop 0
	v_cvt_pk_bf16_f32 v9, v10, v11
	global_store_dwordx2 v[14:15], v[8:9], off offset:96
	s_barrier
	s_cbranch_vccz .LBB0_351
